# flash loops: QK MFMAs issued in K-fragment arrival order (A chain then B chain, one counted lgkmcnt each), V transposed reads after them
# baseline (speedup 1.0000x reference)
; #define LAS __attribute__((address_space(3)))
; #define MFMA32(a, b, c) __builtin_amdgcn_mfma_f32_32x32x16_bf16((a), (b), (c), 0, 0, 0)
; DI s16x4 vtr(const LAS char* p) { return __builtin_bit_cast(s16x4, __builtin_amdgcn_ds_read_tr16_b64_v4i16((LAS v4i16_t*)p)); }
; template <int DQK, int MODE, class Mask> ...
;     ...
;                 for (int kk = 0; kk < NKS; ++kk) kf[kb][kk] = *(const LAS bf16x8*)(Ks + (32 * kb + r) * KP + (16 * kk + 8 * h) * 2);
;             __builtin_amdgcn_sched_barrier(0);
;             f32x16 s[2];
;             asm volatile("v_mfma_f32_32x32x16_bf16 %0, %1, %2, %3" : "=&v"(s[0]) : "v"(kf[0][0]), "v"(qf[0]), "v"(negm16));
;             asm volatile("v_mfma_f32_32x32x16_bf16 %0, %1, %2, %3" : "=&v"(s[1]) : "v"(kf[1][0]), "v"(qf[0]), "v"(negm16));
; #pragma unroll
;             for (int kk = 1; kk < NKS; ++kk) {
;                 s[0] = MFMA32(kf[0][kk], qf[kk], s[0]);
;                 s[1] = MFMA32(kf[1][kk], qf[kk], s[1]);
;             }
;             __builtin_amdgcn_sched_barrier(0);
;             s16x4 vlo[2][2][2], vhi[2][2][2];
;             if (MODE != 1) {
;                 const int q4 = (lane & 15) >> 2, p4 = lane & 3, blk = (lane >> 4) & 1;
;                 const LAS char* vb0 = Vs + (4 * h + q4) * VP + (16 * blk) * 2 + 8 * p4;
; #pragma unroll
;                 for (int kb = 0; kb < 2; ++kb)
; #pragma unroll
;                     for (int s2 = 0; s2 < 2; ++s2)
; #pragma unroll
;                         for (int d = 0; d < 2; ++d) { const LAS char* vb = vb0 + (32 * kb + 16 * s2) * VP + (32 * d) * 2; vlo[kb][s2][d] = vtr(vb); vhi[kb][s2][d] = vtr(vb + 8 * VP); }
;             }
;             __builtin_amdgcn_sched_barrier(0);
;             const int key0 = j * 64 + 4 * h;
;             if (mask.needs(j)) {
; #pragma unroll
;                 for (int kb = 0; kb < 2; ++kb)
; #pragma unroll
;                     for (int i = 0; i < 16; ++i) { const int key = key0 + 32 * kb + (i & 3) + 8 * (i >> 2); s[kb][i] = mask(key, j) ? s[kb][i] : -3e30f; }
;             }
.LBB0_1049:
	s_mul_i32 s12, s17, 0x3400
	v_add_u32_e32 v0, s12, v219
	v_mul_u32_u24_e32 v66, 0xd0, v185
	v_add_u32_e32 v70, v0, v66
	v_add_u32_e32 v0, v0, v224
	ds_read_b128 v[66:69], v70
	ds_read_b128 v[134:137], v70 offset:32
	ds_read_b128 v[138:141], v70 offset:64
	ds_read_b128 v[142:145], v70 offset:96
	ds_read_b128 v[146:149], v70 offset:128
	ds_read_b128 v[228:231], v70 offset:160
	ds_read_b128 v[150:153], v0
	ds_read_b128 v[154:157], v0 offset:32
	ds_read_b128 v[158:161], v0 offset:64
	ds_read_b128 v[162:165], v0 offset:96
	ds_read_b128 v[232:235], v0 offset:128
	ds_read_b128 v[236:239], v0 offset:160
	s_waitcnt lgkmcnt(11)
	v_mfma_f32_32x32x16_bf16 v[82:97], v[66:69], v[118:121], v[50:65]
	s_waitcnt lgkmcnt(10)
	v_mfma_f32_32x32x16_bf16 v[82:97], v[134:137], v[98:101], v[82:97]
	s_waitcnt lgkmcnt(9)
	v_mfma_f32_32x32x16_bf16 v[82:97], v[138:141], v[102:105], v[82:97]
	s_waitcnt lgkmcnt(8)
	v_mfma_f32_32x32x16_bf16 v[82:97], v[142:145], v[106:109], v[82:97]
	s_waitcnt lgkmcnt(7)
	v_mfma_f32_32x32x16_bf16 v[82:97], v[146:149], v[110:113], v[82:97]
	s_waitcnt lgkmcnt(6)
	v_mfma_f32_32x32x16_bf16 v[82:97], v[228:231], v[114:117], v[82:97]
	s_waitcnt lgkmcnt(5)
	v_mfma_f32_32x32x16_bf16 v[66:81], v[150:153], v[118:121], v[50:65]
	s_waitcnt lgkmcnt(4)
	v_mfma_f32_32x32x16_bf16 v[66:81], v[154:157], v[98:101], v[66:81]
	s_waitcnt lgkmcnt(3)
	v_mfma_f32_32x32x16_bf16 v[66:81], v[158:161], v[102:105], v[66:81]
	s_waitcnt lgkmcnt(2)
	v_mfma_f32_32x32x16_bf16 v[66:81], v[162:165], v[106:109], v[66:81]
	s_waitcnt lgkmcnt(1)
	v_mfma_f32_32x32x16_bf16 v[66:81], v[232:235], v[110:113], v[66:81]
	s_waitcnt lgkmcnt(0)
	v_mfma_f32_32x32x16_bf16 v[66:81], v[236:239], v[114:117], v[66:81]
	s_mulk_i32 s17, 0x2400
	v_add_u32_e32 v0, s17, v223
	ds_read_b64_tr_b16 v[162:163], v0 offset:26624
	ds_read_b64_tr_b16 v[164:165], v0 offset:27776
	ds_read_b64_tr_b16 v[160:161], v0 offset:27840
	ds_read_b64_tr_b16 v[158:159], v0 offset:26688
	ds_read_b64_tr_b16 v[154:155], v0 offset:28928
	ds_read_b64_tr_b16 v[156:157], v0 offset:30080
	ds_read_b64_tr_b16 v[152:153], v0 offset:30144
	ds_read_b64_tr_b16 v[150:151], v0 offset:28992
	ds_read_b64_tr_b16 v[146:147], v0 offset:31232
	ds_read_b64_tr_b16 v[148:149], v0 offset:32384
	ds_read_b64_tr_b16 v[144:145], v0 offset:32448
	ds_read_b64_tr_b16 v[142:143], v0 offset:31296
	ds_read_b64_tr_b16 v[138:139], v0 offset:33536
	ds_read_b64_tr_b16 v[140:141], v0 offset:34688
	ds_read_b64_tr_b16 v[136:137], v0 offset:34752
	ds_read_b64_tr_b16 v[134:135], v0 offset:33600
	s_cmp_le_i32 s43, s40
	s_cbranch_scc1 .LBB0_1051
	v_add_u32_e32 v0, s43, v184
	v_subrev_u32_e32 v203, 63, v0
	v_cmp_le_i32_e32 vcc, v203, v202
	s_nop 6
	v_cndmask_b32_e32 v82, v252, v82, vcc
	v_cmp_lt_i32_e32 vcc, v203, v202
	v_subrev_u32_e32 v203, 61, v0
	s_nop 0
	v_cndmask_b32_e32 v83, v252, v83, vcc
	v_cmp_le_i32_e32 vcc, v203, v202
	v_subrev_u32_e32 v203, 60, v0
	s_nop 0
	v_cndmask_b32_e32 v84, v252, v84, vcc
	v_cmp_le_i32_e32 vcc, v203, v202
	v_subrev_u32_e32 v203, 55, v0
	s_nop 0
	v_cndmask_b32_e32 v85, v252, v85, vcc
	v_cmp_le_i32_e32 vcc, v203, v202
	v_subrev_u32_e32 v203, 54, v0
	s_nop 0
	v_cndmask_b32_e32 v86, v252, v86, vcc
	v_cmp_le_i32_e32 vcc, v203, v202
	v_subrev_u32_e32 v203, 53, v0
	s_nop 0
	v_cndmask_b32_e32 v87, v252, v87, vcc
	v_cmp_le_i32_e32 vcc, v203, v202
	v_subrev_u32_e32 v203, 52, v0
	s_nop 0
	v_cndmask_b32_e32 v88, v252, v88, vcc
	v_cmp_le_i32_e32 vcc, v203, v202
	v_subrev_u32_e32 v203, 47, v0
	s_nop 0
	v_cndmask_b32_e32 v89, v252, v89, vcc
	v_cmp_le_i32_e32 vcc, v203, v202
	v_subrev_u32_e32 v203, 46, v0
	s_nop 0
	v_cndmask_b32_e32 v90, v252, v90, vcc
	v_cmp_le_i32_e32 vcc, v203, v202
	v_subrev_u32_e32 v203, 45, v0
	s_nop 0
	v_cndmask_b32_e32 v91, v252, v91, vcc
	v_cmp_le_i32_e32 vcc, v203, v202
	v_subrev_u32_e32 v203, 44, v0
	s_nop 0
	v_cndmask_b32_e32 v92, v252, v92, vcc
	v_cmp_le_i32_e32 vcc, v203, v202
	v_subrev_u32_e32 v203, 39, v0
	s_nop 0
	v_cndmask_b32_e32 v93, v252, v93, vcc
	v_cmp_le_i32_e32 vcc, v203, v202
	v_subrev_u32_e32 v203, 38, v0
	s_nop 0
	v_cndmask_b32_e32 v94, v252, v94, vcc
	v_cmp_le_i32_e32 vcc, v203, v202
	v_subrev_u32_e32 v203, 37, v0
	s_nop 0
	v_cndmask_b32_e32 v95, v252, v95, vcc
	v_cmp_le_i32_e32 vcc, v203, v202
	v_subrev_u32_e32 v203, 36, v0
	s_nop 0
	v_cndmask_b32_e32 v96, v252, v96, vcc
	v_cmp_le_i32_e32 vcc, v203, v202
	v_subrev_u32_e32 v203, 31, v0
	s_nop 0
	v_cndmask_b32_e32 v97, v252, v97, vcc
	v_cmp_le_i32_e32 vcc, v203, v202
	v_subrev_u32_e32 v203, 30, v0
	s_nop 0
	v_cndmask_b32_e32 v66, v252, v66, vcc
	v_cmp_le_i32_e32 vcc, v203, v202
	v_subrev_u32_e32 v203, 29, v0
	s_nop 0
	v_cndmask_b32_e32 v67, v252, v67, vcc
	v_cmp_le_i32_e32 vcc, v203, v202
	v_subrev_u32_e32 v203, 28, v0
	s_nop 0
	v_cndmask_b32_e32 v68, v252, v68, vcc
	v_cmp_le_i32_e32 vcc, v203, v202
	v_subrev_u32_e32 v203, 23, v0
	s_nop 0
	v_cndmask_b32_e32 v69, v252, v69, vcc
	v_cmp_le_i32_e32 vcc, v203, v202
	v_subrev_u32_e32 v203, 22, v0
	s_nop 0
	v_cndmask_b32_e32 v70, v252, v70, vcc
	v_cmp_le_i32_e32 vcc, v203, v202
	v_subrev_u32_e32 v203, 21, v0
	s_nop 0
	v_cndmask_b32_e32 v71, v252, v71, vcc
	v_cmp_le_i32_e32 vcc, v203, v202
	v_subrev_u32_e32 v203, 20, v0
	s_nop 0
	v_cndmask_b32_e32 v72, v252, v72, vcc
	v_cmp_le_i32_e32 vcc, v203, v202
	v_add_u32_e32 v203, -15, v0
	s_nop 0
	v_cndmask_b32_e32 v73, v252, v73, vcc
	v_cmp_le_i32_e32 vcc, v203, v202
	v_add_u32_e32 v203, -14, v0
	s_nop 0
	v_cndmask_b32_e32 v74, v252, v74, vcc
	v_cmp_le_i32_e32 vcc, v203, v202
	v_add_u32_e32 v203, -13, v0
	s_nop 0
	v_cndmask_b32_e32 v75, v252, v75, vcc
	v_cmp_le_i32_e32 vcc, v203, v202
	v_add_u32_e32 v203, -12, v0
	s_nop 0
	v_cndmask_b32_e32 v76, v252, v76, vcc
	v_cmp_le_i32_e32 vcc, v203, v202
	v_add_u32_e32 v203, -7, v0
	s_nop 0
	v_cndmask_b32_e32 v77, v252, v77, vcc
	v_cmp_le_i32_e32 vcc, v203, v202
	v_add_u32_e32 v203, -6, v0
	s_nop 0
	v_cndmask_b32_e32 v78, v252, v78, vcc
	v_cmp_le_i32_e32 vcc, v203, v202
	v_add_u32_e32 v203, -5, v0
	v_add_u32_e32 v0, -4, v0
	v_cndmask_b32_e32 v79, v252, v79, vcc
	v_cmp_le_i32_e32 vcc, v203, v202
	s_nop 1
	v_cndmask_b32_e32 v80, v252, v80, vcc
	v_cmp_le_i32_e32 vcc, v0, v202
	s_nop 1
	v_cndmask_b32_e32 v81, v252, v81, vcc

; template <int DQK, int MODE, class Mask> ...
;     ...
;                 for (int kk = 0; kk < NKS; ++kk) kf[kb][kk] = *(const LAS bf16x8*)(Ks + (32 * kb + r) * KP + (16 * kk + 8 * h) * 2);
;             __builtin_amdgcn_sched_barrier(0);
;             f32x16 s[2];
;             asm volatile("v_mfma_f32_32x32x16_bf16 %0, %1, %2, %3" : "=&v"(s[0]) : "v"(kf[0][0]), "v"(qf[0]), "v"(negm16));
;             asm volatile("v_mfma_f32_32x32x16_bf16 %0, %1, %2, %3" : "=&v"(s[1]) : "v"(kf[1][0]), "v"(qf[0]), "v"(negm16));
; #pragma unroll
;             for (int kk = 1; kk < NKS; ++kk) {
;                 s[0] = MFMA32(kf[0][kk], qf[kk], s[0]);
;                 s[1] = MFMA32(kf[1][kk], qf[kk], s[1]);
;             }
;             __builtin_amdgcn_sched_barrier(0);
;             s16x4 vlo[2][2][2], vhi[2][2][2];
;             if (MODE != 1) {
;                 const int q4 = (lane & 15) >> 2, p4 = lane & 3, blk = (lane >> 4) & 1;
;                 const LAS char* vb0 = Vs + (4 * h + q4) * VP + (16 * blk) * 2 + 8 * p4;
; #pragma unroll
;                 for (int kb = 0; kb < 2; ++kb)
; #pragma unroll
;                     for (int s2 = 0; s2 < 2; ++s2)
; #pragma unroll
;                         for (int d = 0; d < 2; ++d) { const LAS char* vb = vb0 + (32 * kb + 16 * s2) * VP + (32 * d) * 2; vlo[kb][s2][d] = vtr(vb); vhi[kb][s2][d] = vtr(vb + 8 * VP); }
;             }
;             __builtin_amdgcn_sched_barrier(0);
;             const int key0 = j * 64 + 4 * h;
;             if (mask.needs(j)) {
; #pragma unroll
;                 for (int kb = 0; kb < 2; ++kb)
; #pragma unroll
;                     for (int i = 0; i < 16; ++i) { const int key = key0 + 32 * kb + (i & 3) + 8 * (i >> 2); s[kb][i] = mask(key, j) ? s[kb][i] : -3e30f; }
;             }
;             const bool on = mask.lane_on(j);
;             if (MODE == 0 || MODE == 1) {
;                 asm volatile("s_nop 15\n\ts_nop 7" : "+v"(s[0]), "+v"(s[1]));
;                 float mt, mu;
;                 asm volatile("v_max3_f32 %0, %1, %2, %3" : "=v"(mt) : "v"(s[0][0]), "v"(s[0][1]), "v"(s[0][2]));
;                 asm volatile("v_max3_f32 %0, %1, %2, %3" : "=v"(mu) : "v"(s[1][0]), "v"(s[1][1]), "v"(s[1][2]));
; #pragma unroll
;                 for (int i = 3; i < 15; i += 2) {
;                     asm volatile("v_max3_f32 %0, %1, %2, %3" : "=v"(mt) : "v"(mt), "v"(s[0][i]), "v"(s[0][i + 1]));
.LBB0_1099:
	s_mul_i32 s13, s12, 0x3400
	v_add_u32_e32 v0, s13, v219
	v_add_u32_e32 v70, v0, v224
	v_add_u32_e32 v0, v0, v225
	ds_read_b128 v[66:69], v70
	ds_read_b128 v[122:125], v70 offset:32
	ds_read_b128 v[126:129], v70 offset:64
	ds_read_b128 v[204:207], v70 offset:96
	ds_read_b128 v[130:133], v0
	ds_read_b128 v[134:137], v0 offset:32
	ds_read_b128 v[138:141], v0 offset:64
	ds_read_b128 v[142:145], v0 offset:96
	s_waitcnt lgkmcnt(7)
	v_mfma_f32_32x32x16_bf16 v[82:97], v[66:69], v[98:101], v[50:65]
	s_waitcnt lgkmcnt(6)
	v_mfma_f32_32x32x16_bf16 v[82:97], v[122:125], v[102:105], v[82:97]
	s_waitcnt lgkmcnt(5)
	v_mfma_f32_32x32x16_bf16 v[82:97], v[126:129], v[106:109], v[82:97]
	s_waitcnt lgkmcnt(4)
	v_mfma_f32_32x32x16_bf16 v[82:97], v[204:207], v[110:113], v[82:97]
	s_waitcnt lgkmcnt(3)
	v_mfma_f32_32x32x16_bf16 v[66:81], v[130:133], v[98:101], v[50:65]
	s_waitcnt lgkmcnt(2)
	v_mfma_f32_32x32x16_bf16 v[66:81], v[134:137], v[102:105], v[66:81]
	s_waitcnt lgkmcnt(1)
	v_mfma_f32_32x32x16_bf16 v[66:81], v[138:141], v[106:109], v[66:81]
	s_waitcnt lgkmcnt(0)
	v_mfma_f32_32x32x16_bf16 v[66:81], v[142:145], v[110:113], v[66:81]
	s_mulk_i32 s12, 0x2400
	v_add_u32_e32 v0, s12, v228
	ds_read_b64_tr_b16 v[150:151], v0 offset:26624
	ds_read_b64_tr_b16 v[152:153], v0 offset:27776
	ds_read_b64_tr_b16 v[148:149], v0 offset:27840
	ds_read_b64_tr_b16 v[146:147], v0 offset:26688
	ds_read_b64_tr_b16 v[142:143], v0 offset:28928
	ds_read_b64_tr_b16 v[144:145], v0 offset:30080
	ds_read_b64_tr_b16 v[140:141], v0 offset:30144
	ds_read_b64_tr_b16 v[138:139], v0 offset:28992
	ds_read_b64_tr_b16 v[134:135], v0 offset:31232
	ds_read_b64_tr_b16 v[136:137], v0 offset:32384
	ds_read_b64_tr_b16 v[132:133], v0 offset:32448
	ds_read_b64_tr_b16 v[130:131], v0 offset:31296
	ds_read_b64_tr_b16 v[126:127], v0 offset:33536
	ds_read_b64_tr_b16 v[128:129], v0 offset:34688
	ds_read_b64_tr_b16 v[124:125], v0 offset:34752
	ds_read_b64_tr_b16 v[122:123], v0 offset:33600
	s_nop 15
	s_nop 7
	v_lshrrev_b64 v[204:205], s18, v[190:191]
	v_max3_f32 v0, v82, v83, v84
	v_max3_f32 v189, v66, v67, v68
	s_mov_b64 s[20:21], -1
	v_max3_f32 v0, v0, v85, v86
	v_max3_f32 v189, v189, v69, v70
	s_nop 0
	v_max3_f32 v0, v0, v87, v88
	v_max3_f32 v189, v189, v71, v72
	s_nop 0
	v_max3_f32 v0, v0, v89, v90
	v_max3_f32 v189, v189, v73, v74
	s_nop 0
	v_max3_f32 v0, v0, v91, v92
	v_max3_f32 v189, v189, v75, v76
	s_nop 0
	v_max3_f32 v0, v0, v93, v94
	v_max3_f32 v189, v189, v77, v78
	s_nop 0
	v_max3_f32 v206, v0, v95, v96
	v_and_b32_e32 v0, 1, v204
	v_max3_f32 v189, v189, v79, v80
	v_cmp_eq_u64_e64 s[12:13], 0, v[0:1]
	v_max3_f32 v204, v206, v97, v81
	s_nop 0
	v_max_f32 v189, v204, v189
	s_nop 0
	v_cndmask_b32_e64 v0, v189, v252, s[12:13]
	v_mov_b32_e32 v189, v0
	s_nop 1
	v_permlane32_swap_b32_e32 v0, v189
	v_max_f32_e32 v189, v189, v189
	v_max_f32_e32 v0, v0, v0
	v_max_f32_e32 v0, v0, v189
	v_cmp_lt_f32_e32 vcc, s60, v0
	v_cmp_lt_f32_e64 s[30:31], s61, v0
	s_andn2_b64 s[30:31], s[30:31], s[16:17]
	s_or_b64 s[20:21], vcc, s[30:31]
	s_mov_b64 s[30:31], s[16:17]
	s_cbranch_scc0 .LBB0_1096
	s_branch .Ltrim_27890

; #define LAS __attribute__((address_space(3)))
; #define MFMA32(a, b, c) __builtin_amdgcn_mfma_f32_32x32x16_bf16((a), (b), (c), 0, 0, 0)
; DI s16x4 vtr(const LAS char* p) { return __builtin_bit_cast(s16x4, __builtin_amdgcn_ds_read_tr16_b64_v4i16((LAS v4i16_t*)p)); }
; template <int DQK, int MODE, class Mask> ...
;     ...
;                 for (int kk = 0; kk < NKS; ++kk) kf[kb][kk] = *(const LAS bf16x8*)(Ks + (32 * kb + r) * KP + (16 * kk + 8 * h) * 2);
;             __builtin_amdgcn_sched_barrier(0);
;             f32x16 s[2];
;             asm volatile("v_mfma_f32_32x32x16_bf16 %0, %1, %2, %3" : "=&v"(s[0]) : "v"(kf[0][0]), "v"(qf[0]), "v"(negm16));
;             asm volatile("v_mfma_f32_32x32x16_bf16 %0, %1, %2, %3" : "=&v"(s[1]) : "v"(kf[1][0]), "v"(qf[0]), "v"(negm16));
; #pragma unroll
;             for (int kk = 1; kk < NKS; ++kk) {
;                 s[0] = MFMA32(kf[0][kk], qf[kk], s[0]);
;                 s[1] = MFMA32(kf[1][kk], qf[kk], s[1]);
;             }
;             __builtin_amdgcn_sched_barrier(0);
;             s16x4 vlo[2][2][2], vhi[2][2][2];
;             if (MODE != 1) {
;                 const int q4 = (lane & 15) >> 2, p4 = lane & 3, blk = (lane >> 4) & 1;
;                 const LAS char* vb0 = Vs + (4 * h + q4) * VP + (16 * blk) * 2 + 8 * p4;
; #pragma unroll
;                 for (int kb = 0; kb < 2; ++kb)
; #pragma unroll
;                     for (int s2 = 0; s2 < 2; ++s2)
; #pragma unroll
;                         for (int d = 0; d < 2; ++d) { const LAS char* vb = vb0 + (32 * kb + 16 * s2) * VP + (32 * d) * 2; vlo[kb][s2][d] = vtr(vb); vhi[kb][s2][d] = vtr(vb + 8 * VP); }
;             }
;             __builtin_amdgcn_sched_barrier(0);
;             const int key0 = j * 64 + 4 * h;
;             if (mask.needs(j)) {
.LBB0_1122:
	s_mul_i32 s17, s16, 0x3400
	v_add_u32_e32 v0, s17, v219
	v_add_u32_e32 v70, v0, v224
	v_add_u32_e32 v0, v0, v225
	ds_read_b128 v[66:69], v70
	ds_read_b128 v[122:125], v70 offset:32
	ds_read_b128 v[126:129], v70 offset:64
	ds_read_b128 v[234:237], v70 offset:96
	ds_read_b128 v[130:133], v0
	ds_read_b128 v[134:137], v0 offset:32
	ds_read_b128 v[138:141], v0 offset:64
	ds_read_b128 v[142:145], v0 offset:96
	s_waitcnt lgkmcnt(7)
	v_mfma_f32_32x32x16_bf16 v[82:97], v[66:69], v[98:101], v[50:65]
	s_waitcnt lgkmcnt(6)
	v_mfma_f32_32x32x16_bf16 v[82:97], v[122:125], v[102:105], v[82:97]
	s_waitcnt lgkmcnt(5)
	v_mfma_f32_32x32x16_bf16 v[82:97], v[126:129], v[106:109], v[82:97]
	s_waitcnt lgkmcnt(4)
	v_mfma_f32_32x32x16_bf16 v[82:97], v[234:237], v[110:113], v[82:97]
	s_waitcnt lgkmcnt(3)
	v_mfma_f32_32x32x16_bf16 v[66:81], v[130:133], v[98:101], v[50:65]
	s_waitcnt lgkmcnt(2)
	v_mfma_f32_32x32x16_bf16 v[66:81], v[134:137], v[102:105], v[66:81]
	s_waitcnt lgkmcnt(1)
	v_mfma_f32_32x32x16_bf16 v[66:81], v[138:141], v[106:109], v[66:81]
	s_waitcnt lgkmcnt(0)
	v_mfma_f32_32x32x16_bf16 v[66:81], v[142:145], v[110:113], v[66:81]
	s_mulk_i32 s16, 0x2400
	v_add_u32_e32 v0, s16, v228
	ds_read_b64_tr_b16 v[150:151], v0 offset:26624
	ds_read_b64_tr_b16 v[152:153], v0 offset:27776
	ds_read_b64_tr_b16 v[148:149], v0 offset:27840
	ds_read_b64_tr_b16 v[146:147], v0 offset:26688
	ds_read_b64_tr_b16 v[142:143], v0 offset:28928
	ds_read_b64_tr_b16 v[144:145], v0 offset:30080
	ds_read_b64_tr_b16 v[140:141], v0 offset:30144
	ds_read_b64_tr_b16 v[138:139], v0 offset:28992
	ds_read_b64_tr_b16 v[134:135], v0 offset:31232
	ds_read_b64_tr_b16 v[136:137], v0 offset:32384
	ds_read_b64_tr_b16 v[132:133], v0 offset:32448
	ds_read_b64_tr_b16 v[130:131], v0 offset:31296
	ds_read_b64_tr_b16 v[126:127], v0 offset:33536
	ds_read_b64_tr_b16 v[128:129], v0 offset:34688
	ds_read_b64_tr_b16 v[124:125], v0 offset:34752
	ds_read_b64_tr_b16 v[122:123], v0 offset:33600
	s_cmp_eq_u32 s21, s50
	s_cselect_b64 s[16:17], -1, 0
	s_cmp_eq_u32 s24, s50
	s_cselect_b64 s[18:19], -1, 0
	s_or_b64 s[16:17], s[16:17], s[18:19]
	s_andn2_b64 vcc, exec, s[16:17]
	s_cbranch_vccnz .LBB0_1124
; template <int DQK, int MODE, class Mask> ...
;     ...
;             if (mask.needs(j)) {
; #pragma unroll
;                 for (int kb = 0; kb < 2; ++kb)
; #pragma unroll
;                     for (int i = 0; i < 16; ++i) { const int key = key0 + 32 * kb + (i & 3) + 8 * (i >> 2); s[kb][i] = mask(key, j) ? s[kb][i] : -3e30f; }
;             }
	v_cmp_le_i32_e32 vcc, v208, v188
	v_cmp_gt_i32_e64 s[16:17], v208, v183
	s_and_b64 vcc, vcc, s[16:17]
	s_nop 1
	v_cndmask_b32_e32 v82, v252, v82, vcc
	v_cmp_lt_i32_e32 vcc, v208, v188
	v_cmp_ge_i32_e64 s[16:17], v208, v183
	s_and_b64 vcc, vcc, s[16:17]
	v_add_u32_e32 v0, 2, v208
	v_cndmask_b32_e32 v83, v252, v83, vcc
	v_cmp_le_i32_e32 vcc, v0, v188
	v_cmp_gt_i32_e64 s[16:17], v0, v183
	s_and_b64 vcc, vcc, s[16:17]
	v_add_u32_e32 v0, 3, v208
	v_cndmask_b32_e32 v84, v252, v84, vcc
	v_cmp_le_i32_e32 vcc, v0, v188
	v_cmp_gt_i32_e64 s[16:17], v0, v183
	s_and_b64 vcc, vcc, s[16:17]
	v_add_u32_e32 v0, 8, v208
	v_cndmask_b32_e32 v85, v252, v85, vcc
	v_cmp_le_i32_e32 vcc, v0, v188
	v_cmp_gt_i32_e64 s[16:17], v0, v183
	s_and_b64 vcc, vcc, s[16:17]
	v_add_u32_e32 v0, 9, v208
	v_cndmask_b32_e32 v86, v252, v86, vcc
	v_cmp_le_i32_e32 vcc, v0, v188
	v_cmp_gt_i32_e64 s[16:17], v0, v183
	s_and_b64 vcc, vcc, s[16:17]
	v_add_u32_e32 v0, 10, v208
	v_cndmask_b32_e32 v87, v252, v87, vcc
	v_cmp_le_i32_e32 vcc, v0, v188
	v_cmp_gt_i32_e64 s[16:17], v0, v183
	s_and_b64 vcc, vcc, s[16:17]
	v_add_u32_e32 v0, 11, v208
	v_cndmask_b32_e32 v88, v252, v88, vcc
	v_cmp_le_i32_e32 vcc, v0, v188
	v_cmp_gt_i32_e64 s[16:17], v0, v183
	s_and_b64 vcc, vcc, s[16:17]
	v_add_u32_e32 v0, 16, v208
	v_cndmask_b32_e32 v89, v252, v89, vcc
	v_cmp_le_i32_e32 vcc, v0, v188
	v_cmp_gt_i32_e64 s[16:17], v0, v183
	s_and_b64 vcc, vcc, s[16:17]
	v_add_u32_e32 v0, 17, v208
	v_cndmask_b32_e32 v90, v252, v90, vcc
	v_cmp_le_i32_e32 vcc, v0, v188
	v_cmp_gt_i32_e64 s[16:17], v0, v183
	s_and_b64 vcc, vcc, s[16:17]
	v_add_u32_e32 v0, 18, v208
	v_cndmask_b32_e32 v91, v252, v91, vcc
	v_cmp_le_i32_e32 vcc, v0, v188
	v_cmp_gt_i32_e64 s[16:17], v0, v183
	s_and_b64 vcc, vcc, s[16:17]
	v_add_u32_e32 v0, 19, v208
	v_cndmask_b32_e32 v92, v252, v92, vcc
	v_cmp_le_i32_e32 vcc, v0, v188
	v_cmp_gt_i32_e64 s[16:17], v0, v183
	s_and_b64 vcc, vcc, s[16:17]
	v_add_u32_e32 v0, 24, v208
	v_cndmask_b32_e32 v93, v252, v93, vcc
	v_cmp_le_i32_e32 vcc, v0, v188
	v_cmp_gt_i32_e64 s[16:17], v0, v183
	s_and_b64 vcc, vcc, s[16:17]
	v_add_u32_e32 v0, 25, v208
	v_cndmask_b32_e32 v94, v252, v94, vcc
	v_cmp_le_i32_e32 vcc, v0, v188
	v_cmp_gt_i32_e64 s[16:17], v0, v183
	s_and_b64 vcc, vcc, s[16:17]
	v_add_u32_e32 v0, 26, v208
	v_cndmask_b32_e32 v95, v252, v95, vcc
	v_cmp_le_i32_e32 vcc, v0, v188
	v_cmp_gt_i32_e64 s[16:17], v0, v183
	s_and_b64 vcc, vcc, s[16:17]
	v_add_u32_e32 v0, 27, v208
	v_cndmask_b32_e32 v96, v252, v96, vcc
	v_cmp_le_i32_e32 vcc, v0, v188
	v_cmp_gt_i32_e64 s[16:17], v0, v183
	s_and_b64 vcc, vcc, s[16:17]
	v_add_u32_e32 v0, 32, v208
	v_cndmask_b32_e32 v97, v252, v97, vcc
	v_cmp_le_i32_e32 vcc, v0, v188
	v_cmp_gt_i32_e64 s[16:17], v0, v183
	s_and_b64 vcc, vcc, s[16:17]
	v_add_u32_e32 v0, 33, v208
	v_cndmask_b32_e32 v66, v252, v66, vcc
	v_cmp_le_i32_e32 vcc, v0, v188
	v_cmp_gt_i32_e64 s[16:17], v0, v183
	s_and_b64 vcc, vcc, s[16:17]
	v_add_u32_e32 v0, 34, v208
	v_cndmask_b32_e32 v67, v252, v67, vcc
	v_cmp_le_i32_e32 vcc, v0, v188
	v_cmp_gt_i32_e64 s[16:17], v0, v183
	s_and_b64 vcc, vcc, s[16:17]
	v_add_u32_e32 v0, 35, v208
	v_cndmask_b32_e32 v68, v252, v68, vcc
	v_cmp_le_i32_e32 vcc, v0, v188
	v_cmp_gt_i32_e64 s[16:17], v0, v183
	s_and_b64 vcc, vcc, s[16:17]
	v_add_u32_e32 v0, 40, v208
	v_cndmask_b32_e32 v69, v252, v69, vcc
	v_cmp_le_i32_e32 vcc, v0, v188
	v_cmp_gt_i32_e64 s[16:17], v0, v183
	s_and_b64 vcc, vcc, s[16:17]
	v_add_u32_e32 v0, 41, v208
	v_cndmask_b32_e32 v70, v252, v70, vcc
	v_cmp_le_i32_e32 vcc, v0, v188
	v_cmp_gt_i32_e64 s[16:17], v0, v183
	s_and_b64 vcc, vcc, s[16:17]
	v_add_u32_e32 v0, 42, v208
	v_cndmask_b32_e32 v71, v252, v71, vcc
	v_cmp_le_i32_e32 vcc, v0, v188
	v_cmp_gt_i32_e64 s[16:17], v0, v183
	s_and_b64 vcc, vcc, s[16:17]
	v_add_u32_e32 v0, 43, v208
	v_cndmask_b32_e32 v72, v252, v72, vcc
	v_cmp_le_i32_e32 vcc, v0, v188
	v_cmp_gt_i32_e64 s[16:17], v0, v183
	s_and_b64 vcc, vcc, s[16:17]
	v_add_u32_e32 v0, 48, v208
	v_cndmask_b32_e32 v73, v252, v73, vcc
	v_cmp_le_i32_e32 vcc, v0, v188
	v_cmp_gt_i32_e64 s[16:17], v0, v183
	s_and_b64 vcc, vcc, s[16:17]
	v_add_u32_e32 v0, 49, v208
	v_cndmask_b32_e32 v74, v252, v74, vcc
	v_cmp_le_i32_e32 vcc, v0, v188
	v_cmp_gt_i32_e64 s[16:17], v0, v183
	s_and_b64 vcc, vcc, s[16:17]
	v_add_u32_e32 v0, 50, v208
	v_cndmask_b32_e32 v75, v252, v75, vcc
	v_cmp_le_i32_e32 vcc, v0, v188
	v_cmp_gt_i32_e64 s[16:17], v0, v183
	s_and_b64 vcc, vcc, s[16:17]
	v_add_u32_e32 v0, 51, v208
	v_cndmask_b32_e32 v76, v252, v76, vcc
	v_cmp_le_i32_e32 vcc, v0, v188
	v_cmp_gt_i32_e64 s[16:17], v0, v183
	s_and_b64 vcc, vcc, s[16:17]
	v_add_u32_e32 v0, 56, v208
	v_cndmask_b32_e32 v77, v252, v77, vcc
	v_cmp_le_i32_e32 vcc, v0, v188
	v_cmp_gt_i32_e64 s[16:17], v0, v183
	s_and_b64 vcc, vcc, s[16:17]
	v_add_u32_e32 v0, 57, v208
	v_cndmask_b32_e32 v78, v252, v78, vcc
	v_cmp_le_i32_e32 vcc, v0, v188
	v_cmp_gt_i32_e64 s[16:17], v0, v183
	s_and_b64 vcc, vcc, s[16:17]
	v_add_u32_e32 v0, 58, v208
	v_cndmask_b32_e32 v79, v252, v79, vcc
	v_cmp_le_i32_e32 vcc, v0, v188
	v_cmp_gt_i32_e64 s[16:17], v0, v183
	s_and_b64 vcc, vcc, s[16:17]
	v_add_u32_e32 v0, 59, v208
	v_cndmask_b32_e32 v80, v252, v80, vcc
	v_cmp_le_i32_e32 vcc, v0, v188
	v_cmp_gt_i32_e64 s[16:17], v0, v183
	s_and_b64 vcc, vcc, s[16:17]
	v_cndmask_b32_e32 v81, v252, v81, vcc
